# dilated attention: non-temporal hint on the running-state (o accumulator) stores and reloads between branches
# baseline (speedup 1.0000x reference)
.Lpf_L1:
	s_mov_b32 s99, 0
	s_lshr_b32 s98, s100, 2
	s_and_b32 s101, s100, 3
	s_or_b32 s101, s101, s37
	s_add_i32 s12, s100, s38
	s_and_b64 vcc, s[26:27], exec
	s_cselect_b32 s98, s98, s100
	s_cselect_b32 s101, s101, s36
	s_and_b64 vcc, s[28:29], exec
	s_cselect_b32 s98, 0, s98
	s_cselect_b32 s101, s12, s101
	s_lshl_b32 s101, s101, 8
	s_add_i32 s12, s101, s9
	v_or_b32_e32 v224, s12, v122
	v_ashrrev_i32_e32 v225, 31, v224
	v_lshlrev_b64 v[224:225], s41, v[224:225]
	v_lshl_add_u64 v[224:225], v[224:225], 0, s[98:99]
	v_mad_u64_u32 v[226:227], s[12:13], v224, s33, v[104:105]
	v_mad_i32_i24 v227, v225, s33, v227
	global_load_dwordx4 v[142:145], v[226:227], off
	global_load_dwordx4 v[146:149], v[226:227], off offset:32
	global_load_dwordx4 v[150:153], v[226:227], off offset:64
	global_load_dwordx4 v[154:157], v[226:227], off offset:96
	s_andn2_b64 vcc, exec, s[22:23]
	s_cbranch_vccnz .Lpfns_L1
	v_lshlrev_b64 v[226:227], 11, v[224:225]
	v_lshl_add_u64 v[226:227], v[110:111], 0, v[226:227]
	global_load_dwordx2 v[206:207], v[226:227], off nt
	global_load_dwordx2 v[208:209], v[226:227], off offset:16 nt
	global_load_dwordx2 v[210:211], v[226:227], off offset:32 nt
	global_load_dwordx2 v[212:213], v[226:227], off offset:48 nt
	global_load_dwordx2 v[214:215], v[226:227], off offset:64 nt
	global_load_dwordx2 v[216:217], v[226:227], off offset:80 nt
	global_load_dwordx2 v[218:219], v[226:227], off offset:96 nt
	global_load_dwordx2 v[220:221], v[226:227], off offset:112 nt
	v_lshlrev_b64 v[228:229], 7, v[224:225]
	v_lshl_add_u64 v[228:229], s[20:21], 0, v[228:229]
	global_load_dword v222, v[228:229], off
	v_mov_b32_e32 v223, 0
	s_and_saveexec_b64 s[12:13], s[10:11]
	global_load_dword v223, v[228:229], off offset:4
	s_or_b64 exec, exec, s[12:13]

.LBB0_1732:
	v_cvt_pk_bf16_f32 v4, v32, v33
	v_cvt_pk_bf16_f32 v5, v34, v35
	s_nop 3
	v_cvt_pk_bf16_f32 v6, v16, v17
	v_cvt_pk_bf16_f32 v7, v18, v19
	global_store_dwordx2 v[118:119], v[4:5], off nt
	global_store_dwordx2 v[118:119], v[6:7], off offset:64 nt
	v_cvt_pk_bf16_f32 v4, v36, v37
	v_cvt_pk_bf16_f32 v5, v38, v39
	v_cvt_pk_bf16_f32 v6, v20, v21
	v_cvt_pk_bf16_f32 v7, v22, v23
	global_store_dwordx2 v[118:119], v[4:5], off offset:16 nt
	global_store_dwordx2 v[118:119], v[6:7], off offset:80 nt
	v_cvt_pk_bf16_f32 v4, v40, v41
	v_cvt_pk_bf16_f32 v5, v42, v43
	v_cvt_pk_bf16_f32 v6, v24, v25
	v_cvt_pk_bf16_f32 v7, v26, v27
	global_store_dwordx2 v[118:119], v[4:5], off offset:32 nt
	global_store_dwordx2 v[118:119], v[6:7], off offset:96 nt
	v_cvt_pk_bf16_f32 v4, v44, v45
	v_cvt_pk_bf16_f32 v5, v46, v47
	v_cvt_pk_bf16_f32 v6, v28, v29
	v_cvt_pk_bf16_f32 v7, v30, v31
	global_store_dwordx2 v[118:119], v[4:5], off offset:48 nt
	global_store_dwordx2 v[118:119], v[6:7], off offset:112 nt
	s_and_saveexec_b64 s[12:13], s[10:11]
	s_cbranch_execz .LBB0_1734
	v_lshlrev_b64 v[4:5], 7, v[116:117]
	v_lshl_add_u64 v[4:5], s[20:21], 0, v[4:5]
	global_store_dwordx2 v[4:5], v[2:3], off

.Lpf_L3:
	s_mov_b32 s99, 0
	s_lshr_b32 s98, s100, 2
	s_and_b32 s101, s100, 3
	s_or_b32 s101, s101, s37
	s_add_i32 s10, s100, s38
	s_and_b64 vcc, s[24:25], exec
	s_cselect_b32 s98, s98, s100
	s_cselect_b32 s101, s101, s36
	s_and_b64 vcc, s[26:27], exec
	s_cselect_b32 s98, 0, s98
	s_cselect_b32 s101, s10, s101
	s_lshl_b32 s101, s101, 8
	s_add_i32 s10, s101, s29
	v_or_b32_e32 v224, s10, v122
	v_ashrrev_i32_e32 v225, 31, v224
	v_lshlrev_b64 v[224:225], s41, v[224:225]
	v_lshl_add_u64 v[224:225], v[224:225], 0, s[98:99]
	v_mad_u64_u32 v[226:227], s[10:11], v224, s33, v[104:105]
	v_mad_i32_i24 v227, v225, s33, v227
	global_load_dwordx4 v[142:145], v[226:227], off
	global_load_dwordx4 v[146:149], v[226:227], off offset:32
	global_load_dwordx4 v[150:153], v[226:227], off offset:64
	global_load_dwordx4 v[154:157], v[226:227], off offset:96
	s_andn2_b64 vcc, exec, s[20:21]
	s_cbranch_vccnz .Lpfns_L3
	v_lshlrev_b64 v[226:227], 11, v[224:225]
	v_lshl_add_u64 v[226:227], v[110:111], 0, v[226:227]
	global_load_dwordx2 v[206:207], v[226:227], off nt
	global_load_dwordx2 v[208:209], v[226:227], off offset:16 nt
	global_load_dwordx2 v[210:211], v[226:227], off offset:32 nt
	global_load_dwordx2 v[212:213], v[226:227], off offset:48 nt
	global_load_dwordx2 v[214:215], v[226:227], off offset:64 nt
	global_load_dwordx2 v[216:217], v[226:227], off offset:80 nt
	global_load_dwordx2 v[218:219], v[226:227], off offset:96 nt
	global_load_dwordx2 v[220:221], v[226:227], off offset:112 nt
	v_lshlrev_b64 v[228:229], 7, v[224:225]
	v_lshl_add_u64 v[228:229], s[18:19], 0, v[228:229]
	global_load_dword v222, v[228:229], off
	v_mov_b32_e32 v223, 0
	s_and_saveexec_b64 s[10:11], s[8:9]
	global_load_dword v223, v[228:229], off offset:4
	s_or_b64 exec, exec, s[10:11]

.LBB0_3833:
	v_cvt_pk_bf16_f32 v4, v32, v33
	v_cvt_pk_bf16_f32 v5, v34, v35
	s_nop 3
	v_cvt_pk_bf16_f32 v6, v16, v17
	v_cvt_pk_bf16_f32 v7, v18, v19
	global_store_dwordx2 v[118:119], v[4:5], off nt
	global_store_dwordx2 v[118:119], v[6:7], off offset:64 nt
	v_cvt_pk_bf16_f32 v4, v36, v37
	v_cvt_pk_bf16_f32 v5, v38, v39
	v_cvt_pk_bf16_f32 v6, v20, v21
	v_cvt_pk_bf16_f32 v7, v22, v23
	global_store_dwordx2 v[118:119], v[4:5], off offset:16 nt
	global_store_dwordx2 v[118:119], v[6:7], off offset:80 nt
	v_cvt_pk_bf16_f32 v4, v40, v41
	v_cvt_pk_bf16_f32 v5, v42, v43
	v_cvt_pk_bf16_f32 v6, v24, v25
	v_cvt_pk_bf16_f32 v7, v26, v27
	global_store_dwordx2 v[118:119], v[4:5], off offset:32 nt
	global_store_dwordx2 v[118:119], v[6:7], off offset:96 nt
	v_cvt_pk_bf16_f32 v4, v44, v45
	v_cvt_pk_bf16_f32 v5, v46, v47
	v_cvt_pk_bf16_f32 v6, v28, v29
	v_cvt_pk_bf16_f32 v7, v30, v31
	global_store_dwordx2 v[118:119], v[4:5], off offset:48 nt
	global_store_dwordx2 v[118:119], v[6:7], off offset:112 nt
	s_and_saveexec_b64 s[10:11], s[8:9]
	s_cbranch_execz .LBB0_3835
	v_lshlrev_b64 v[4:5], 7, v[116:117]
	v_lshl_add_u64 v[4:5], s[18:19], 0, v[4:5]
	global_store_dwordx2 v[4:5], v[2:3], off
